# v110 + fused final epilogue pass 2: next half's loads issued before the previous half's stores (renamed dests, counted vmcnt)
# speedup vs baseline: 1.0024x; 1.0024x over previous
.LBB0_1382:
	s_or_b64 exec, exec, s[22:23]
	s_barrier
	global_load_dword v149, v[132:133], off sc1
	global_load_dwordx4 v[198:201], v[152:153], off
	v_lshl_add_u64 v[134:135], v[150:151], 2, s[4:5]
	global_load_dwordx4 v[202:205], v[134:135], off
	global_load_dwordx4 v[206:209], v[134:135], off offset:16
	v_lshl_add_u64 v[154:155], v[154:155], 0, v[150:151]
	v_lshl_add_u64 v[156:157], v[154:155], 2, s[6:7]
	v_readlane_b32 s16, v254, 24
	v_readlane_b32 s17, v254, 25
	s_and_b64 vcc, exec, s[44:45]
	s_waitcnt vmcnt(3)
	v_fmamk_f32 v149, v149, 0x39800000, v1
	s_waitcnt lgkmcnt(0)
	v_rsq_f32_e32 v212, v149
	s_waitcnt vmcnt(2)
	v_lshlrev_b32_e32 v154, 16, v198
	v_and_b32_e32 v155, 0xffff0000, v198
	v_lshlrev_b32_e32 v198, 16, v199
	v_and_b32_e32 v199, 0xffff0000, v199
	v_lshlrev_b32_e32 v210, 16, v200
	v_and_b32_e32 v211, 0xffff0000, v200
	v_lshlrev_b32_e32 v200, 16, v201
	v_and_b32_e32 v201, 0xffff0000, v201
	v_pk_add_f32 v[126:127], v[126:127], v[154:155]
	v_pk_add_f32 v[128:129], v[128:129], v[198:199]
	v_pk_add_f32 v[122:123], v[122:123], v[210:211]
	v_pk_add_f32 v[124:125], v[124:125], v[200:201]
	v_pk_mul_f32 v[126:127], v[212:213], v[126:127] op_sel_hi:[0,1]
	v_pk_mul_f32 v[128:129], v[212:213], v[128:129] op_sel_hi:[0,1]
	v_pk_mul_f32 v[154:155], v[212:213], v[122:123] op_sel_hi:[0,1]
	v_pk_mul_f32 v[198:199], v[212:213], v[124:125] op_sel_hi:[0,1]
	s_waitcnt vmcnt(1)
	v_pk_mul_f32 v[124:125], v[204:205], v[128:129]
	v_pk_mul_f32 v[122:123], v[202:203], v[126:127]
	s_waitcnt vmcnt(0)
	v_pk_mul_f32 v[128:129], v[208:209], v[198:199]
	v_pk_mul_f32 v[126:127], v[206:207], v[154:155]
	global_load_dwordx4 v[220:223], v[152:153], off offset:256
	global_load_dwordx4 v[224:227], v[134:135], off offset:512
	global_load_dwordx4 v[242:245], v[134:135], off offset:528
	global_store_dwordx4 v[156:157], v[122:125], off
	global_store_dwordx4 v[156:157], v[126:129], off offset:16
	s_nop 1
	v_lshl_add_u64 v[162:163], v[162:163], 2, s[16:17]
	s_waitcnt vmcnt(4)
	v_mov_b32_e32 v122, v220
	v_mov_b32_e32 v123, v221
	v_mov_b32_e32 v124, v222
	v_mov_b32_e32 v125, v223
	v_lshlrev_b32_e32 v198, 16, v122
	v_and_b32_e32 v199, 0xffff0000, v122
	v_lshlrev_b32_e32 v122, 16, v123
	v_and_b32_e32 v123, 0xffff0000, v123
	v_lshlrev_b32_e32 v200, 16, v124
	v_and_b32_e32 v201, 0xffff0000, v124
	v_lshlrev_b32_e32 v124, 16, v125
	v_and_b32_e32 v125, 0xffff0000, v125
	v_pk_add_f32 v[118:119], v[118:119], v[198:199]
	v_pk_add_f32 v[120:121], v[120:121], v[122:123]
	v_pk_add_f32 v[114:115], v[114:115], v[200:201]
	v_pk_add_f32 v[116:117], v[116:117], v[124:125]
	v_pk_mul_f32 v[118:119], v[212:213], v[118:119] op_sel_hi:[0,1]
	v_pk_mul_f32 v[120:121], v[212:213], v[120:121] op_sel_hi:[0,1]
	v_pk_mul_f32 v[122:123], v[212:213], v[114:115] op_sel_hi:[0,1]
	v_pk_mul_f32 v[124:125], v[212:213], v[116:117] op_sel_hi:[0,1]
	s_waitcnt vmcnt(3)
	v_mov_b32_e32 v126, v224
	v_mov_b32_e32 v127, v225
	v_mov_b32_e32 v128, v226
	v_mov_b32_e32 v129, v227
	v_pk_mul_f32 v[116:117], v[128:129], v[120:121]
	v_pk_mul_f32 v[114:115], v[126:127], v[118:119]
	s_waitcnt vmcnt(2)
	v_mov_b32_e32 v152, v242
	v_mov_b32_e32 v153, v243
	v_mov_b32_e32 v154, v244
	v_mov_b32_e32 v155, v245
	v_pk_mul_f32 v[120:121], v[154:155], v[124:125]
	v_pk_mul_f32 v[118:119], v[152:153], v[122:123]
	global_load_dword v246, v[162:163], off sc1
	global_load_dwordx4 v[220:223], v[158:159], off
	global_load_dwordx4 v[224:227], v[134:135], off
	global_load_dwordx4 v[242:245], v[134:135], off offset:16
	global_store_dwordx4 v[156:157], v[114:117], off offset:512
	global_store_dwordx4 v[156:157], v[118:121], off offset:528
	s_nop 1
	v_lshl_add_u64 v[126:127], v[160:161], 0, v[150:151]
	v_lshl_add_u64 v[126:127], v[126:127], 2, s[6:7]
	s_waitcnt vmcnt(5)
	v_mov_b32_e32 v128, v246
	v_fmamk_f32 v149, v128, 0x39800000, v1
	v_rsq_f32_e32 v154, v149
	s_waitcnt vmcnt(4)
	v_mov_b32_e32 v114, v220
	v_mov_b32_e32 v115, v221
	v_mov_b32_e32 v116, v222
	v_mov_b32_e32 v117, v223
	v_lshlrev_b32_e32 v128, 16, v114
	v_and_b32_e32 v129, 0xffff0000, v114
	v_lshlrev_b32_e32 v114, 16, v115
	v_and_b32_e32 v115, 0xffff0000, v115
	v_lshlrev_b32_e32 v152, 16, v116
	v_and_b32_e32 v153, 0xffff0000, v116
	v_lshlrev_b32_e32 v116, 16, v117
	v_and_b32_e32 v117, 0xffff0000, v117
	v_pk_add_f32 v[110:111], v[110:111], v[128:129]
	v_pk_add_f32 v[112:113], v[112:113], v[114:115]
	v_pk_add_f32 v[106:107], v[106:107], v[152:153]
	v_pk_add_f32 v[108:109], v[108:109], v[116:117]
	v_pk_mul_f32 v[110:111], v[154:155], v[110:111] op_sel_hi:[0,1]
	v_pk_mul_f32 v[112:113], v[154:155], v[112:113] op_sel_hi:[0,1]
	v_pk_mul_f32 v[114:115], v[154:155], v[106:107] op_sel_hi:[0,1]
	v_pk_mul_f32 v[116:117], v[154:155], v[108:109] op_sel_hi:[0,1]
	s_waitcnt vmcnt(3)
	v_mov_b32_e32 v118, v224
	v_mov_b32_e32 v119, v225
	v_mov_b32_e32 v120, v226
	v_mov_b32_e32 v121, v227
	v_pk_mul_f32 v[108:109], v[120:121], v[112:113]
	v_pk_mul_f32 v[106:107], v[118:119], v[110:111]
	s_waitcnt vmcnt(2)
	v_mov_b32_e32 v122, v242
	v_mov_b32_e32 v123, v243
	v_mov_b32_e32 v124, v244
	v_mov_b32_e32 v125, v245
	v_pk_mul_f32 v[112:113], v[124:125], v[116:117]
	v_pk_mul_f32 v[110:111], v[122:123], v[114:115]
	global_load_dwordx4 v[220:223], v[158:159], off offset:256
	global_load_dwordx4 v[224:227], v[134:135], off offset:512
	global_load_dwordx4 v[242:245], v[134:135], off offset:528
	global_store_dwordx4 v[126:127], v[106:109], off
	global_store_dwordx4 v[126:127], v[110:113], off offset:16
	s_nop 1
	v_lshl_add_u64 v[118:119], v[168:169], 2, s[16:17]
	s_waitcnt vmcnt(4)
	v_mov_b32_e32 v106, v220
	v_mov_b32_e32 v107, v221
	v_mov_b32_e32 v108, v222
	v_mov_b32_e32 v109, v223
	v_lshlrev_b32_e32 v120, 16, v106
	v_and_b32_e32 v121, 0xffff0000, v106
	v_lshlrev_b32_e32 v106, 16, v107
	v_and_b32_e32 v107, 0xffff0000, v107
	v_lshlrev_b32_e32 v122, 16, v108
	v_and_b32_e32 v123, 0xffff0000, v108
	v_lshlrev_b32_e32 v108, 16, v109
	v_and_b32_e32 v109, 0xffff0000, v109
	v_pk_add_f32 v[102:103], v[102:103], v[120:121]
	v_pk_add_f32 v[104:105], v[104:105], v[106:107]
	v_pk_add_f32 v[98:99], v[98:99], v[122:123]
	v_pk_add_f32 v[100:101], v[100:101], v[108:109]
	v_pk_mul_f32 v[102:103], v[154:155], v[102:103] op_sel_hi:[0,1]
	v_pk_mul_f32 v[104:105], v[154:155], v[104:105] op_sel_hi:[0,1]
	v_pk_mul_f32 v[106:107], v[154:155], v[98:99] op_sel_hi:[0,1]
	v_pk_mul_f32 v[108:109], v[154:155], v[100:101] op_sel_hi:[0,1]
	s_waitcnt vmcnt(3)
	v_mov_b32_e32 v110, v224
	v_mov_b32_e32 v111, v225
	v_mov_b32_e32 v112, v226
	v_mov_b32_e32 v113, v227
	v_pk_mul_f32 v[100:101], v[112:113], v[104:105]
	v_pk_mul_f32 v[98:99], v[110:111], v[102:103]
	s_waitcnt vmcnt(2)
	v_mov_b32_e32 v114, v242
	v_mov_b32_e32 v115, v243
	v_mov_b32_e32 v116, v244
	v_mov_b32_e32 v117, v245
	v_pk_mul_f32 v[104:105], v[116:117], v[108:109]
	v_pk_mul_f32 v[102:103], v[114:115], v[106:107]
	global_load_dword v246, v[118:119], off sc1
	global_load_dwordx4 v[220:223], v[164:165], off
	global_load_dwordx4 v[224:227], v[134:135], off
	global_load_dwordx4 v[242:245], v[134:135], off offset:16
	global_store_dwordx4 v[126:127], v[98:101], off offset:512
	global_store_dwordx4 v[126:127], v[102:105], off offset:528
	s_nop 1
	v_lshl_add_u64 v[110:111], v[166:167], 0, v[150:151]
	v_lshl_add_u64 v[110:111], v[110:111], 2, s[6:7]
	s_waitcnt vmcnt(5)
	v_mov_b32_e32 v112, v246
	v_fmamk_f32 v116, v112, 0x39800000, v1
	v_rsq_f32_e32 v116, v116
	s_waitcnt vmcnt(4)
	v_mov_b32_e32 v98, v220
	v_mov_b32_e32 v99, v221
	v_mov_b32_e32 v100, v222
	v_mov_b32_e32 v101, v223
	v_lshlrev_b32_e32 v112, 16, v98
	v_and_b32_e32 v113, 0xffff0000, v98
	v_lshlrev_b32_e32 v98, 16, v99
	v_and_b32_e32 v99, 0xffff0000, v99
	v_lshlrev_b32_e32 v114, 16, v100
	v_and_b32_e32 v115, 0xffff0000, v100
	v_lshlrev_b32_e32 v100, 16, v101
	v_and_b32_e32 v101, 0xffff0000, v101
	v_pk_add_f32 v[94:95], v[94:95], v[112:113]
	v_pk_add_f32 v[96:97], v[96:97], v[98:99]
	v_pk_add_f32 v[90:91], v[90:91], v[114:115]
	v_pk_add_f32 v[92:93], v[92:93], v[100:101]
	v_pk_mul_f32 v[94:95], v[116:117], v[94:95] op_sel_hi:[0,1]
	v_pk_mul_f32 v[96:97], v[116:117], v[96:97] op_sel_hi:[0,1]
	v_pk_mul_f32 v[98:99], v[116:117], v[90:91] op_sel_hi:[0,1]
	v_pk_mul_f32 v[100:101], v[116:117], v[92:93] op_sel_hi:[0,1]
	s_waitcnt vmcnt(3)
	v_mov_b32_e32 v102, v224
	v_mov_b32_e32 v103, v225
	v_mov_b32_e32 v104, v226
	v_mov_b32_e32 v105, v227
	v_pk_mul_f32 v[92:93], v[104:105], v[96:97]
	v_pk_mul_f32 v[90:91], v[102:103], v[94:95]
	s_waitcnt vmcnt(2)
	v_mov_b32_e32 v106, v242
	v_mov_b32_e32 v107, v243
	v_mov_b32_e32 v108, v244
	v_mov_b32_e32 v109, v245
	v_pk_mul_f32 v[96:97], v[108:109], v[100:101]
	v_pk_mul_f32 v[94:95], v[106:107], v[98:99]
	global_load_dwordx4 v[220:223], v[164:165], off offset:256
	global_load_dwordx4 v[224:227], v[134:135], off offset:512
	global_load_dwordx4 v[242:245], v[134:135], off offset:528
	global_store_dwordx4 v[110:111], v[90:93], off
	global_store_dwordx4 v[110:111], v[94:97], off offset:16
	s_nop 1
	v_lshl_add_u64 v[102:103], v[174:175], 2, s[16:17]
	s_mov_b64 s[16:17], -1
	s_waitcnt vmcnt(4)
	v_mov_b32_e32 v90, v220
	v_mov_b32_e32 v91, v221
	v_mov_b32_e32 v92, v222
	v_mov_b32_e32 v93, v223
	v_lshlrev_b32_e32 v104, 16, v90
	v_and_b32_e32 v105, 0xffff0000, v90
	v_lshlrev_b32_e32 v90, 16, v91
	v_and_b32_e32 v91, 0xffff0000, v91
	v_lshlrev_b32_e32 v106, 16, v92
	v_and_b32_e32 v107, 0xffff0000, v92
	v_lshlrev_b32_e32 v92, 16, v93
	v_and_b32_e32 v93, 0xffff0000, v93
	v_pk_add_f32 v[86:87], v[86:87], v[104:105]
	v_pk_add_f32 v[88:89], v[88:89], v[90:91]
	v_pk_add_f32 v[82:83], v[82:83], v[106:107]
	v_pk_add_f32 v[84:85], v[84:85], v[92:93]
	v_pk_mul_f32 v[86:87], v[116:117], v[86:87] op_sel_hi:[0,1]
	v_pk_mul_f32 v[88:89], v[116:117], v[88:89] op_sel_hi:[0,1]
	v_pk_mul_f32 v[90:91], v[116:117], v[82:83] op_sel_hi:[0,1]
	v_pk_mul_f32 v[92:93], v[116:117], v[84:85] op_sel_hi:[0,1]
	s_waitcnt vmcnt(3)
	v_mov_b32_e32 v94, v224
	v_mov_b32_e32 v95, v225
	v_mov_b32_e32 v96, v226
	v_mov_b32_e32 v97, v227
	v_pk_mul_f32 v[84:85], v[96:97], v[88:89]
	v_pk_mul_f32 v[82:83], v[94:95], v[86:87]
	s_waitcnt vmcnt(2)
	v_mov_b32_e32 v98, v242
	v_mov_b32_e32 v99, v243
	v_mov_b32_e32 v100, v244
	v_mov_b32_e32 v101, v245
	v_pk_mul_f32 v[88:89], v[100:101], v[92:93]
	v_pk_mul_f32 v[86:87], v[98:99], v[90:91]
	global_load_dword v246, v[102:103], off sc1
	global_load_dwordx4 v[220:223], v[170:171], off
	global_load_dwordx4 v[224:227], v[134:135], off
	global_load_dwordx4 v[242:245], v[134:135], off offset:16
	global_store_dwordx4 v[110:111], v[82:85], off offset:512
	global_store_dwordx4 v[110:111], v[86:89], off offset:528
	s_nop 1
	v_lshl_add_u64 v[94:95], v[172:173], 0, v[150:151]
	v_lshl_add_u64 v[94:95], v[94:95], 2, s[6:7]
	s_waitcnt vmcnt(5)
	v_mov_b32_e32 v96, v246
	v_fmamk_f32 v100, v96, 0x39800000, v1
	v_rsq_f32_e32 v100, v100
	s_waitcnt vmcnt(4)
	v_mov_b32_e32 v82, v220
	v_mov_b32_e32 v83, v221
	v_mov_b32_e32 v84, v222
	v_mov_b32_e32 v85, v223
	v_lshlrev_b32_e32 v96, 16, v82
	v_and_b32_e32 v97, 0xffff0000, v82
	v_lshlrev_b32_e32 v82, 16, v83
	v_and_b32_e32 v83, 0xffff0000, v83
	v_lshlrev_b32_e32 v98, 16, v84
	v_and_b32_e32 v99, 0xffff0000, v84
	v_lshlrev_b32_e32 v84, 16, v85
	v_and_b32_e32 v85, 0xffff0000, v85
	v_pk_add_f32 v[78:79], v[78:79], v[96:97]
	v_pk_add_f32 v[80:81], v[80:81], v[82:83]
	v_pk_add_f32 v[74:75], v[74:75], v[98:99]
	v_pk_add_f32 v[76:77], v[76:77], v[84:85]
	v_pk_mul_f32 v[78:79], v[100:101], v[78:79] op_sel_hi:[0,1]
	v_pk_mul_f32 v[80:81], v[100:101], v[80:81] op_sel_hi:[0,1]
	v_pk_mul_f32 v[82:83], v[100:101], v[74:75] op_sel_hi:[0,1]
	v_pk_mul_f32 v[84:85], v[100:101], v[76:77] op_sel_hi:[0,1]
	s_waitcnt vmcnt(3)
	v_mov_b32_e32 v86, v224
	v_mov_b32_e32 v87, v225
	v_mov_b32_e32 v88, v226
	v_mov_b32_e32 v89, v227
	v_pk_mul_f32 v[76:77], v[88:89], v[80:81]
	v_pk_mul_f32 v[74:75], v[86:87], v[78:79]
	s_waitcnt vmcnt(2)
	v_mov_b32_e32 v90, v242
	v_mov_b32_e32 v91, v243
	v_mov_b32_e32 v92, v244
	v_mov_b32_e32 v93, v245
	v_pk_mul_f32 v[80:81], v[92:93], v[84:85]
	v_pk_mul_f32 v[78:79], v[90:91], v[82:83]
	global_load_dwordx4 v[220:223], v[170:171], off offset:256
	global_load_dwordx4 v[224:227], v[134:135], off offset:512
	global_load_dwordx4 v[242:245], v[134:135], off offset:528
	global_store_dwordx4 v[94:95], v[74:77], off
	global_store_dwordx4 v[94:95], v[78:81], off offset:16
	s_nop 1
	s_waitcnt vmcnt(4)
	v_mov_b32_e32 v74, v220
	v_mov_b32_e32 v75, v221
	v_mov_b32_e32 v76, v222
	v_mov_b32_e32 v77, v223
	v_lshlrev_b32_e32 v86, 16, v74
	v_and_b32_e32 v87, 0xffff0000, v74
	v_lshlrev_b32_e32 v74, 16, v75
	v_and_b32_e32 v75, 0xffff0000, v75
	v_lshlrev_b32_e32 v88, 16, v76
	v_and_b32_e32 v89, 0xffff0000, v76
	v_lshlrev_b32_e32 v76, 16, v77
	v_and_b32_e32 v77, 0xffff0000, v77
	v_pk_add_f32 v[70:71], v[70:71], v[86:87]
	v_pk_add_f32 v[72:73], v[72:73], v[74:75]
	v_pk_add_f32 v[66:67], v[66:67], v[88:89]
	v_pk_add_f32 v[68:69], v[68:69], v[76:77]
	v_pk_mul_f32 v[70:71], v[100:101], v[70:71] op_sel_hi:[0,1]
	v_pk_mul_f32 v[72:73], v[100:101], v[72:73] op_sel_hi:[0,1]
	v_pk_mul_f32 v[74:75], v[100:101], v[66:67] op_sel_hi:[0,1]
	v_pk_mul_f32 v[76:77], v[100:101], v[68:69] op_sel_hi:[0,1]
	s_waitcnt vmcnt(3)
	v_mov_b32_e32 v78, v224
	v_mov_b32_e32 v79, v225
	v_mov_b32_e32 v80, v226
	v_mov_b32_e32 v81, v227
	v_pk_mul_f32 v[68:69], v[80:81], v[72:73]
	v_pk_mul_f32 v[66:67], v[78:79], v[70:71]
	s_waitcnt vmcnt(2)
	v_mov_b32_e32 v82, v242
	v_mov_b32_e32 v83, v243
	v_mov_b32_e32 v84, v244
	v_mov_b32_e32 v85, v245
	v_pk_mul_f32 v[72:73], v[84:85], v[76:77]
	v_pk_mul_f32 v[70:71], v[82:83], v[74:75]
	global_load_dword v246, v[132:133], off offset:512 sc1
	global_load_dwordx4 v[220:223], v[176:177], off
	global_load_dwordx4 v[224:227], v[134:135], off
	global_load_dwordx4 v[242:245], v[134:135], off offset:16
	global_store_dwordx4 v[94:95], v[66:69], off offset:512
	global_store_dwordx4 v[94:95], v[70:73], off offset:528
	s_nop 1
	v_lshl_add_u64 v[78:79], v[178:179], 0, v[150:151]
	v_lshl_add_u64 v[78:79], v[78:79], 2, s[6:7]
	s_waitcnt vmcnt(5)
	v_mov_b32_e32 v80, v246
	v_fmamk_f32 v84, v80, 0x39800000, v1
	v_rsq_f32_e32 v84, v84
	s_waitcnt vmcnt(4)
	v_mov_b32_e32 v66, v220
	v_mov_b32_e32 v67, v221
	v_mov_b32_e32 v68, v222
	v_mov_b32_e32 v69, v223
	v_lshlrev_b32_e32 v80, 16, v66
	v_and_b32_e32 v81, 0xffff0000, v66
	v_lshlrev_b32_e32 v66, 16, v67
	v_and_b32_e32 v67, 0xffff0000, v67
	v_lshlrev_b32_e32 v82, 16, v68
	v_and_b32_e32 v83, 0xffff0000, v68
	v_lshlrev_b32_e32 v68, 16, v69
	v_and_b32_e32 v69, 0xffff0000, v69
	v_pk_add_f32 v[62:63], v[62:63], v[80:81]
	v_pk_add_f32 v[64:65], v[64:65], v[66:67]
	v_pk_add_f32 v[58:59], v[58:59], v[82:83]
	v_pk_add_f32 v[60:61], v[60:61], v[68:69]
	v_pk_mul_f32 v[62:63], v[84:85], v[62:63] op_sel_hi:[0,1]
	v_pk_mul_f32 v[64:65], v[84:85], v[64:65] op_sel_hi:[0,1]
	v_pk_mul_f32 v[66:67], v[84:85], v[58:59] op_sel_hi:[0,1]
	v_pk_mul_f32 v[68:69], v[84:85], v[60:61] op_sel_hi:[0,1]
	s_waitcnt vmcnt(3)
	v_mov_b32_e32 v70, v224
	v_mov_b32_e32 v71, v225
	v_mov_b32_e32 v72, v226
	v_mov_b32_e32 v73, v227
	v_pk_mul_f32 v[60:61], v[72:73], v[64:65]
	v_pk_mul_f32 v[58:59], v[70:71], v[62:63]
	s_waitcnt vmcnt(2)
	v_mov_b32_e32 v74, v242
	v_mov_b32_e32 v75, v243
	v_mov_b32_e32 v76, v244
	v_mov_b32_e32 v77, v245
	v_pk_mul_f32 v[64:65], v[76:77], v[68:69]
	v_pk_mul_f32 v[62:63], v[74:75], v[66:67]
	global_load_dwordx4 v[220:223], v[176:177], off offset:256
	global_load_dwordx4 v[224:227], v[134:135], off offset:512
	global_load_dwordx4 v[242:245], v[134:135], off offset:528
	global_store_dwordx4 v[78:79], v[58:61], off
	global_store_dwordx4 v[78:79], v[62:65], off offset:16
	s_nop 1
	s_waitcnt vmcnt(4)
	v_mov_b32_e32 v58, v220
	v_mov_b32_e32 v59, v221
	v_mov_b32_e32 v60, v222
	v_mov_b32_e32 v61, v223
	v_lshlrev_b32_e32 v70, 16, v58
	v_and_b32_e32 v71, 0xffff0000, v58
	v_lshlrev_b32_e32 v58, 16, v59
	v_and_b32_e32 v59, 0xffff0000, v59
	v_lshlrev_b32_e32 v72, 16, v60
	v_and_b32_e32 v73, 0xffff0000, v60
	v_lshlrev_b32_e32 v60, 16, v61
	v_and_b32_e32 v61, 0xffff0000, v61
	v_pk_add_f32 v[54:55], v[54:55], v[70:71]
	v_pk_add_f32 v[56:57], v[56:57], v[58:59]
	v_pk_add_f32 v[50:51], v[50:51], v[72:73]
	v_pk_add_f32 v[52:53], v[52:53], v[60:61]
	v_pk_mul_f32 v[54:55], v[84:85], v[54:55] op_sel_hi:[0,1]
	v_pk_mul_f32 v[56:57], v[84:85], v[56:57] op_sel_hi:[0,1]
	v_pk_mul_f32 v[58:59], v[84:85], v[50:51] op_sel_hi:[0,1]
	v_pk_mul_f32 v[60:61], v[84:85], v[52:53] op_sel_hi:[0,1]
	s_waitcnt vmcnt(3)
	v_mov_b32_e32 v62, v224
	v_mov_b32_e32 v63, v225
	v_mov_b32_e32 v64, v226
	v_mov_b32_e32 v65, v227
	v_pk_mul_f32 v[52:53], v[64:65], v[56:57]
	v_pk_mul_f32 v[50:51], v[62:63], v[54:55]
	s_waitcnt vmcnt(2)
	v_mov_b32_e32 v66, v242
	v_mov_b32_e32 v67, v243
	v_mov_b32_e32 v68, v244
	v_mov_b32_e32 v69, v245
	v_pk_mul_f32 v[56:57], v[68:69], v[60:61]
	v_pk_mul_f32 v[54:55], v[66:67], v[58:59]
	global_load_dword v246, v[132:133], off offset:576 sc1
	global_load_dwordx4 v[220:223], v[180:181], off
	global_load_dwordx4 v[224:227], v[134:135], off
	global_load_dwordx4 v[242:245], v[134:135], off offset:16
	global_store_dwordx4 v[78:79], v[50:53], off offset:512
	global_store_dwordx4 v[78:79], v[54:57], off offset:528
	s_nop 1
	v_lshl_add_u64 v[62:63], v[182:183], 0, v[150:151]
	v_lshl_add_u64 v[62:63], v[62:63], 2, s[6:7]
	s_waitcnt vmcnt(5)
	v_mov_b32_e32 v64, v246
	v_fmamk_f32 v68, v64, 0x39800000, v1
	v_rsq_f32_e32 v68, v68
	s_waitcnt vmcnt(4)
	v_mov_b32_e32 v50, v220
	v_mov_b32_e32 v51, v221
	v_mov_b32_e32 v52, v222
	v_mov_b32_e32 v53, v223
	v_lshlrev_b32_e32 v64, 16, v50
	v_and_b32_e32 v65, 0xffff0000, v50
	v_lshlrev_b32_e32 v50, 16, v51
	v_and_b32_e32 v51, 0xffff0000, v51
	v_lshlrev_b32_e32 v66, 16, v52
	v_and_b32_e32 v67, 0xffff0000, v52
	v_lshlrev_b32_e32 v52, 16, v53
	v_and_b32_e32 v53, 0xffff0000, v53
	v_pk_add_f32 v[46:47], v[46:47], v[64:65]
	v_pk_add_f32 v[48:49], v[48:49], v[50:51]
	v_pk_add_f32 v[42:43], v[42:43], v[66:67]
	v_pk_add_f32 v[44:45], v[44:45], v[52:53]
	v_pk_mul_f32 v[46:47], v[68:69], v[46:47] op_sel_hi:[0,1]
	v_pk_mul_f32 v[48:49], v[68:69], v[48:49] op_sel_hi:[0,1]
	v_pk_mul_f32 v[50:51], v[68:69], v[42:43] op_sel_hi:[0,1]
	v_pk_mul_f32 v[52:53], v[68:69], v[44:45] op_sel_hi:[0,1]
	s_waitcnt vmcnt(3)
	v_mov_b32_e32 v54, v224
	v_mov_b32_e32 v55, v225
	v_mov_b32_e32 v56, v226
	v_mov_b32_e32 v57, v227
	v_pk_mul_f32 v[44:45], v[56:57], v[48:49]
	v_pk_mul_f32 v[42:43], v[54:55], v[46:47]
	s_waitcnt vmcnt(2)
	v_mov_b32_e32 v58, v242
	v_mov_b32_e32 v59, v243
	v_mov_b32_e32 v60, v244
	v_mov_b32_e32 v61, v245
	v_pk_mul_f32 v[48:49], v[60:61], v[52:53]
	v_pk_mul_f32 v[46:47], v[58:59], v[50:51]
	global_load_dwordx4 v[220:223], v[180:181], off offset:256
	global_load_dwordx4 v[224:227], v[134:135], off offset:512
	global_load_dwordx4 v[242:245], v[134:135], off offset:528
	global_store_dwordx4 v[62:63], v[42:45], off
	global_store_dwordx4 v[62:63], v[46:49], off offset:16
	s_nop 1
	s_waitcnt vmcnt(4)
	v_mov_b32_e32 v42, v220
	v_mov_b32_e32 v43, v221
	v_mov_b32_e32 v44, v222
	v_mov_b32_e32 v45, v223
	v_lshlrev_b32_e32 v54, 16, v42
	v_and_b32_e32 v55, 0xffff0000, v42
	v_lshlrev_b32_e32 v42, 16, v43
	v_and_b32_e32 v43, 0xffff0000, v43
	v_lshlrev_b32_e32 v56, 16, v44
	v_and_b32_e32 v57, 0xffff0000, v44
	v_lshlrev_b32_e32 v44, 16, v45
	v_and_b32_e32 v45, 0xffff0000, v45
	v_pk_add_f32 v[38:39], v[38:39], v[54:55]
	v_pk_add_f32 v[40:41], v[40:41], v[42:43]
	v_pk_add_f32 v[34:35], v[34:35], v[56:57]
	v_pk_add_f32 v[36:37], v[36:37], v[44:45]
	v_pk_mul_f32 v[38:39], v[68:69], v[38:39] op_sel_hi:[0,1]
	v_pk_mul_f32 v[40:41], v[68:69], v[40:41] op_sel_hi:[0,1]
	v_pk_mul_f32 v[42:43], v[68:69], v[34:35] op_sel_hi:[0,1]
	v_pk_mul_f32 v[44:45], v[68:69], v[36:37] op_sel_hi:[0,1]
	s_waitcnt vmcnt(3)
	v_mov_b32_e32 v46, v224
	v_mov_b32_e32 v47, v225
	v_mov_b32_e32 v48, v226
	v_mov_b32_e32 v49, v227
	v_pk_mul_f32 v[36:37], v[48:49], v[40:41]
	v_pk_mul_f32 v[34:35], v[46:47], v[38:39]
	s_waitcnt vmcnt(2)
	v_mov_b32_e32 v50, v242
	v_mov_b32_e32 v51, v243
	v_mov_b32_e32 v52, v244
	v_mov_b32_e32 v53, v245
	v_pk_mul_f32 v[40:41], v[52:53], v[44:45]
	v_pk_mul_f32 v[38:39], v[50:51], v[42:43]
	global_load_dword v246, v[132:133], off offset:640 sc1
	global_load_dwordx4 v[220:223], v[184:185], off
	global_load_dwordx4 v[224:227], v[134:135], off
	global_load_dwordx4 v[242:245], v[134:135], off offset:16
	global_store_dwordx4 v[62:63], v[34:37], off offset:512
	global_store_dwordx4 v[62:63], v[38:41], off offset:528
	s_nop 1
	v_lshl_add_u64 v[46:47], v[186:187], 0, v[150:151]
	v_lshl_add_u64 v[46:47], v[46:47], 2, s[6:7]
	s_waitcnt vmcnt(5)
	v_mov_b32_e32 v48, v246
	v_fmamk_f32 v52, v48, 0x39800000, v1
	v_rsq_f32_e32 v52, v52
	s_waitcnt vmcnt(4)
	v_mov_b32_e32 v34, v220
	v_mov_b32_e32 v35, v221
	v_mov_b32_e32 v36, v222
	v_mov_b32_e32 v37, v223
	v_lshlrev_b32_e32 v48, 16, v34
	v_and_b32_e32 v49, 0xffff0000, v34
	v_lshlrev_b32_e32 v34, 16, v35
	v_and_b32_e32 v35, 0xffff0000, v35
	v_lshlrev_b32_e32 v50, 16, v36
	v_and_b32_e32 v51, 0xffff0000, v36
	v_lshlrev_b32_e32 v36, 16, v37
	v_and_b32_e32 v37, 0xffff0000, v37
	v_pk_add_f32 v[30:31], v[30:31], v[48:49]
	v_pk_add_f32 v[32:33], v[32:33], v[34:35]
	v_pk_add_f32 v[26:27], v[26:27], v[50:51]
	v_pk_add_f32 v[28:29], v[28:29], v[36:37]
	v_pk_mul_f32 v[30:31], v[52:53], v[30:31] op_sel_hi:[0,1]
	v_pk_mul_f32 v[32:33], v[52:53], v[32:33] op_sel_hi:[0,1]
	v_pk_mul_f32 v[34:35], v[52:53], v[26:27] op_sel_hi:[0,1]
	v_pk_mul_f32 v[36:37], v[52:53], v[28:29] op_sel_hi:[0,1]
	s_waitcnt vmcnt(3)
	v_mov_b32_e32 v38, v224
	v_mov_b32_e32 v39, v225
	v_mov_b32_e32 v40, v226
	v_mov_b32_e32 v41, v227
	v_pk_mul_f32 v[28:29], v[40:41], v[32:33]
	v_pk_mul_f32 v[26:27], v[38:39], v[30:31]
	s_waitcnt vmcnt(2)
	v_mov_b32_e32 v42, v242
	v_mov_b32_e32 v43, v243
	v_mov_b32_e32 v44, v244
	v_mov_b32_e32 v45, v245
	v_pk_mul_f32 v[32:33], v[44:45], v[36:37]
	v_pk_mul_f32 v[30:31], v[42:43], v[34:35]
	global_load_dwordx4 v[220:223], v[184:185], off offset:256
	global_load_dwordx4 v[224:227], v[134:135], off offset:512
	global_load_dwordx4 v[242:245], v[134:135], off offset:528
	global_store_dwordx4 v[46:47], v[26:29], off
	global_store_dwordx4 v[46:47], v[30:33], off offset:16
	s_nop 1
	s_waitcnt vmcnt(4)
	v_mov_b32_e32 v26, v220
	v_mov_b32_e32 v27, v221
	v_mov_b32_e32 v28, v222
	v_mov_b32_e32 v29, v223
	v_lshlrev_b32_e32 v38, 16, v26
	v_and_b32_e32 v39, 0xffff0000, v26
	v_lshlrev_b32_e32 v26, 16, v27
	v_and_b32_e32 v27, 0xffff0000, v27
	v_lshlrev_b32_e32 v40, 16, v28
	v_and_b32_e32 v41, 0xffff0000, v28
	v_lshlrev_b32_e32 v28, 16, v29
	v_and_b32_e32 v29, 0xffff0000, v29
	v_pk_add_f32 v[22:23], v[22:23], v[38:39]
	v_pk_add_f32 v[24:25], v[24:25], v[26:27]
	v_pk_add_f32 v[18:19], v[18:19], v[40:41]
	v_pk_add_f32 v[20:21], v[20:21], v[28:29]
	v_pk_mul_f32 v[22:23], v[52:53], v[22:23] op_sel_hi:[0,1]
	v_pk_mul_f32 v[24:25], v[52:53], v[24:25] op_sel_hi:[0,1]
	v_pk_mul_f32 v[26:27], v[52:53], v[18:19] op_sel_hi:[0,1]
	v_pk_mul_f32 v[28:29], v[52:53], v[20:21] op_sel_hi:[0,1]
	s_waitcnt vmcnt(3)
	v_mov_b32_e32 v30, v224
	v_mov_b32_e32 v31, v225
	v_mov_b32_e32 v32, v226
	v_mov_b32_e32 v33, v227
	v_pk_mul_f32 v[20:21], v[32:33], v[24:25]
	v_pk_mul_f32 v[18:19], v[30:31], v[22:23]
	s_waitcnt vmcnt(2)
	v_mov_b32_e32 v34, v242
	v_mov_b32_e32 v35, v243
	v_mov_b32_e32 v36, v244
	v_mov_b32_e32 v37, v245
	v_pk_mul_f32 v[24:25], v[36:37], v[28:29]
	v_pk_mul_f32 v[22:23], v[34:35], v[26:27]
	global_load_dword v246, v[132:133], off offset:704 sc1
	global_load_dwordx4 v[220:223], v[188:189], off
	global_load_dwordx4 v[224:227], v[134:135], off
	global_load_dwordx4 v[242:245], v[134:135], off offset:16
	global_store_dwordx4 v[46:47], v[18:21], off offset:512
	global_store_dwordx4 v[46:47], v[22:25], off offset:528
	s_nop 1
	v_lshl_add_u64 v[30:31], v[190:191], 0, v[150:151]
	v_lshl_add_u64 v[30:31], v[30:31], 2, s[6:7]
	s_waitcnt vmcnt(5)
	v_mov_b32_e32 v32, v246
	v_fmamk_f32 v36, v32, 0x39800000, v1
	v_rsq_f32_e32 v36, v36
	s_waitcnt vmcnt(4)
	v_mov_b32_e32 v18, v220
	v_mov_b32_e32 v19, v221
	v_mov_b32_e32 v20, v222
	v_mov_b32_e32 v21, v223
	v_lshlrev_b32_e32 v32, 16, v18
	v_and_b32_e32 v33, 0xffff0000, v18
	v_lshlrev_b32_e32 v18, 16, v19
	v_and_b32_e32 v19, 0xffff0000, v19
	v_lshlrev_b32_e32 v34, 16, v20
	v_and_b32_e32 v35, 0xffff0000, v20
	v_lshlrev_b32_e32 v20, 16, v21
	v_and_b32_e32 v21, 0xffff0000, v21
	v_pk_add_f32 v[14:15], v[14:15], v[32:33]
	v_pk_add_f32 v[16:17], v[16:17], v[18:19]
	v_pk_add_f32 v[10:11], v[10:11], v[34:35]
	v_pk_add_f32 v[12:13], v[12:13], v[20:21]
	v_pk_mul_f32 v[14:15], v[36:37], v[14:15] op_sel_hi:[0,1]
	v_pk_mul_f32 v[16:17], v[36:37], v[16:17] op_sel_hi:[0,1]
	v_pk_mul_f32 v[18:19], v[36:37], v[10:11] op_sel_hi:[0,1]
	v_pk_mul_f32 v[20:21], v[36:37], v[12:13] op_sel_hi:[0,1]
	s_waitcnt vmcnt(3)
	v_mov_b32_e32 v22, v224
	v_mov_b32_e32 v23, v225
	v_mov_b32_e32 v24, v226
	v_mov_b32_e32 v25, v227
	v_pk_mul_f32 v[12:13], v[24:25], v[16:17]
	v_pk_mul_f32 v[10:11], v[22:23], v[14:15]
	s_waitcnt vmcnt(2)
	v_mov_b32_e32 v26, v242
	v_mov_b32_e32 v27, v243
	v_mov_b32_e32 v28, v244
	v_mov_b32_e32 v29, v245
	v_pk_mul_f32 v[16:17], v[28:29], v[20:21]
	v_pk_mul_f32 v[14:15], v[26:27], v[18:19]
	global_load_dwordx4 v[220:223], v[188:189], off offset:256
	global_load_dwordx4 v[224:227], v[134:135], off offset:512
	global_load_dwordx4 v[242:245], v[134:135], off offset:528
	global_store_dwordx4 v[30:31], v[10:13], off
	global_store_dwordx4 v[30:31], v[14:17], off offset:16
	s_nop 1
	s_waitcnt vmcnt(4)
	v_mov_b32_e32 v10, v220
	v_mov_b32_e32 v11, v221
	v_mov_b32_e32 v12, v222
	v_mov_b32_e32 v13, v223
	v_lshlrev_b32_e32 v22, 16, v10
	v_and_b32_e32 v23, 0xffff0000, v10
	v_lshlrev_b32_e32 v10, 16, v11
	v_and_b32_e32 v11, 0xffff0000, v11
	v_lshlrev_b32_e32 v24, 16, v12
	v_and_b32_e32 v25, 0xffff0000, v12
	v_lshlrev_b32_e32 v12, 16, v13
	v_and_b32_e32 v13, 0xffff0000, v13
	v_pk_add_f32 v[6:7], v[6:7], v[22:23]
	v_pk_add_f32 v[8:9], v[8:9], v[10:11]
	v_pk_add_f32 v[2:3], v[2:3], v[24:25]
	v_pk_add_f32 v[4:5], v[4:5], v[12:13]
	v_pk_mul_f32 v[6:7], v[36:37], v[6:7] op_sel_hi:[0,1]
	v_pk_mul_f32 v[8:9], v[36:37], v[8:9] op_sel_hi:[0,1]
	v_pk_mul_f32 v[10:11], v[36:37], v[2:3] op_sel_hi:[0,1]
	v_pk_mul_f32 v[12:13], v[36:37], v[4:5] op_sel_hi:[0,1]
	s_waitcnt vmcnt(3)
	v_mov_b32_e32 v14, v224
	v_mov_b32_e32 v15, v225
	v_mov_b32_e32 v16, v226
	v_mov_b32_e32 v17, v227
	v_pk_mul_f32 v[4:5], v[16:17], v[8:9]
	v_pk_mul_f32 v[2:3], v[14:15], v[6:7]
	s_waitcnt vmcnt(2)
	v_mov_b32_e32 v18, v242
	v_mov_b32_e32 v19, v243
	v_mov_b32_e32 v20, v244
	v_mov_b32_e32 v21, v245
	v_pk_mul_f32 v[8:9], v[20:21], v[12:13]
	v_pk_mul_f32 v[6:7], v[18:19], v[10:11]
	global_store_dwordx4 v[30:31], v[2:5], off offset:512
	global_store_dwordx4 v[30:31], v[6:9], off offset:528
	s_cbranch_vccnz .LBB0_1342
	s_andn2_b64 vcc, exec, s[40:41]
	s_cbranch_vccnz .LBB0_1341
	s_barrier
	s_branch .LBB0_1341
